# one static s_setprio 1 for the lagging wave group during the attention phase (reset to 0 after)
# speedup vs baseline: 1.0090x; 1.0090x over previous
.Latt_lead_8:
	s_mov_b32 s53, 0
	s_cmp_eq_u32 s68, 0
	s_cbranch_scc1 .Latt_prio_skip
	s_setprio 1
.Latt_prio_skip:
.Latt_blk:
	s_lshr_b32 s11, s53, 4
	s_and_b32 s12, s53, 15
	s_lshl_b32 s20, s11, 1
	s_lshl_b32 s13, s64, 4
	s_add_i32 s13, s13, s12
	s_lshr_b32 s14, s12, 2
	s_and_b32 s15, s12, 3
	s_lshl_b32 s16, s64, 2
	s_add_i32 s15, s16, s15
	s_cmp_eq_u32 s11, 1
	s_cselect_b32 s21, s14, 0
	s_cselect_b32 s24, s15, s13
	s_cmp_eq_u32 s11, 2
	s_cselect_b32 s21, s12, s21
	s_cselect_b32 s24, s64, s24
	s_add_i32 s4, s53, 1
	s_min_u32 s4, s4, 47
	s_lshr_b32 s11, s4, 4
	s_and_b32 s12, s4, 15
	s_lshl_b32 s28, s11, 1
	s_lshl_b32 s13, s64, 4
	s_add_i32 s13, s13, s12
	s_lshr_b32 s14, s12, 2
	s_and_b32 s15, s12, 3
	s_lshl_b32 s16, s64, 2
	s_add_i32 s15, s16, s15
	s_cmp_eq_u32 s11, 1
	s_cselect_b32 s29, s14, 0
	s_cselect_b32 s30, s15, s13
	s_cmp_eq_u32 s11, 2
	s_cselect_b32 s29, s12, s29
	s_cselect_b32 s30, s64, s30
	s_lshr_b32 s11, s4, 4
	s_and_b32 s12, s4, 15
	s_and_b32 s13, s12, 3
	s_cmp_lg_u32 s12, 0
	s_cselect_b32 s14, 1, 0
	s_lshr_b32 s15, s12, 2
	s_and_b32 s16, s12, 3
	s_add_i32 s15, s15, s16
	s_add_i32 s15, s15, 1
	s_and_b32 s15, s15, 3
	s_cmp_lg_u32 s16, 0
	s_cselect_b32 s16, 1, 0
	s_cmp_eq_u32 s11, 1
	s_cselect_b32 s13, s15, s13
	s_cselect_b32 s14, s16, s14
	s_and_b32 s15, s12, 1
	s_lshl_b32 s15, s15, 1
	s_add_i32 s15, s15, 1
	s_cmp_eq_u32 s11, 2
	s_cselect_b32 s88, s15, s13
	s_cselect_b32 s89, 0, s14
	s_lshl_b32 s5, s88, 7
	s_lshl_b32 s6, s67, 3
	s_add_i32 s5, s5, s6
	s_add_i32 s6, s30, -1
	s_lshl_b32 s6, s6, 7
	s_cmp_eq_u32 s89, 1
	s_cbranch_scc1 .Latt_half_10
	s_add_i32 s7, s5, 0
	s_and_b32 s7, s7, 511
	s_lshl_b32 s7, s7, 7
	s_add_i32 m0, s7, s48
	s_add_i32 s7, s6, 0
	v_add_u32_e32 v0, s7, v14
	v_lshlrev_b32_e32 v0, s28, v0
	v_add_u32_e32 v0, s29, v0
	v_max_i32_e32 v0, 0, v0
	v_lshl_or_b32 v2, v0, 7, v15
	v_lshl_add_u64 v[38:39], s[46:47], 0, v[2:3]
	global_load_lds_dwordx4 v[38:39], off nt
	s_add_i32 s7, s5, 64
	s_and_b32 s7, s7, 511
	s_lshl_b32 s7, s7, 7
	s_add_i32 m0, s7, s48
	s_add_i32 s7, s6, 64
	v_add_u32_e32 v0, s7, v14
	v_lshlrev_b32_e32 v0, s28, v0
	v_add_u32_e32 v0, s29, v0
	v_max_i32_e32 v0, 0, v0
	v_lshl_or_b32 v2, v0, 7, v15
	v_lshl_add_u64 v[40:41], s[46:47], 0, v[2:3]
	global_load_lds_dwordx4 v[40:41], off nt

.LBB0_203:
	s_setprio 0
	v_readlane_b32 s88, v249, 48
	v_readlane_b32 s76, v249, 56
	v_readlane_b32 s96, v249, 59
	v_readlane_b32 s98, v249, 61
	v_readlane_b32 s64, v249, 40
	v_readlane_b32 s66, v249, 42
	v_readlane_b32 s68, v249, 44
	v_readlane_b32 s24, v249, 46
	v_readlane_b32 s16, v248, 3
	s_mov_b64 s[4:5], 0
	v_readlane_b32 s89, v249, 49
	v_readlane_b32 s90, v249, 50
	v_readlane_b32 s91, v249, 51
	v_readlane_b32 s92, v249, 52
	v_readlane_b32 s93, v249, 53
	v_readlane_b32 s94, v249, 54
	v_readlane_b32 s95, v249, 55
	v_readlane_b32 s77, v249, 57
	v_readlane_b32 s75, v249, 58
	v_readlane_b32 s97, v249, 60
	v_readlane_b32 s99, v249, 62
	v_readlane_b32 s65, v249, 41
	v_readlane_b32 s67, v249, 43
	v_readlane_b32 s69, v249, 45
	v_readlane_b32 s25, v249, 47
	v_readlane_b32 s81, v249, 63
	s_movk_i32 s87, 0x161
	v_readlane_b32 s28, v249, 30
	v_readlane_b32 s46, v248, 2
	v_readlane_b32 s17, v248, 4
	v_readlane_b32 s10, v248, 5
